# attention: per-tile barrier right before the 3rd P.V MFMA of sub-step 1, behind all 16 exps and converts (six MFMAs follow the release)
# baseline (speedup 1.0000x reference)
; __device__ __forceinline__ unsigned pk2(float lo, float hi) { return pg8::cvt_pk_bf16(lo, hi); }
; #define MFMA32(a, b, c) __builtin_amdgcn_mfma_f32_32x32x16_bf16((a), (b), (c), 0, 0, 0)
; __device__ __forceinline__ void attn_phase(const Args& a, int l, bool with_ctx, unsigned char* lds) {
;     ...
;                 for (int r = 0; r < 16; ++r) { S[r] = __builtin_amdgcn_exp2f(S[r]); ps += S[r]; }
;                 lrun += ps;
;                 u32x4 p0, p1;
;                 p0.x = pk2(S[0], S[1]); p0.y = pk2(S[2], S[3]); p0.z = pk2(S[4], S[5]); p0.w = pk2(S[6], S[7]);
;                 p1.x = pk2(S[8], S[9]); p1.y = pk2(S[10], S[11]); p1.z = pk2(S[12], S[13]); p1.w = pk2(S[14], S[15]);
;                 const bf16x8 pa0 = __builtin_bit_cast(bf16x8, p0), pa1 = __builtin_bit_cast(bf16x8, p1);
; #pragma unroll
;                 for (int j = 0; j < 4; ++j) O[j] = MFMA32(vf[2 * j], pa0, O[j]);
; #pragma unroll
;                 for (int j = 0; j < 4; ++j) O[j] = MFMA32(vf[2 * j + 1], pa1, O[j]);
;             }
;             if (t + 1 < nt) { unsigned char* kd = kdst + (cur ^ 1) * BUF; unsigned char* vd = vdst + (cur ^ 1) * BUF;
;                 *(u32x4*)kd = k0; *(u32x4*)(kd + 9216) = k1; *(u32x4*)vd = v0; *(u32x4*)(vd + 9216) = v1; }
;             __syncthreads();
.LBB0_412:
	v_exp_f32_e32 v67, v68
	v_exp_f32_e32 v68, v69
	v_exp_f32_e32 v69, v70
	v_exp_f32_e32 v70, v71
	v_exp_f32_e32 v71, v72
	v_exp_f32_e32 v72, v73
	v_exp_f32_e32 v73, v74
	v_exp_f32_e32 v74, v75
	v_cvt_pk_bf16_f32 v184, v67, v68
	v_cvt_pk_bf16_f32 v185, v69, v70
	v_cvt_pk_bf16_f32 v186, v71, v72
	v_cvt_pk_bf16_f32 v187, v73, v74
	v_exp_f32_e32 v75, v76
	v_exp_f32_e32 v76, v77
	s_waitcnt lgkmcnt(11)
	v_mfma_f32_32x32x16_bf16 v[50:65], v[136:139], v[184:187], v[50:65]
	v_exp_f32_e32 v77, v78
	v_exp_f32_e32 v78, v79
	v_exp_f32_e32 v79, v80
	v_exp_f32_e32 v80, v81
	v_exp_f32_e32 v81, v82
	v_exp_f32_e32 v82, v83
	v_cvt_pk_bf16_f32 v214, v75, v76
	s_waitcnt lgkmcnt(9)
	v_mfma_f32_32x32x16_bf16 v[34:49], v[140:143], v[184:187], v[34:49]
	v_cvt_pk_bf16_f32 v215, v77, v78
	v_cvt_pk_bf16_f32 v216, v79, v80
	v_cvt_pk_bf16_f32 v217, v81, v82
	s_andn2_b64 vcc, exec, s[10:11]
	s_waitcnt lgkmcnt(0)
	s_barrier
	v_mfma_f32_32x32x16_bf16 v[18:33], v[144:147], v[184:187], v[18:33]
	s_waitcnt lgkmcnt(5)
	v_mfma_f32_32x32x16_bf16 v[2:17], v[132:135], v[184:187], v[2:17]
	v_mfma_f32_32x32x16_bf16 v[50:65], v[116:119], v[214:217], v[50:65]
	v_mfma_f32_32x32x16_bf16 v[34:49], v[120:123], v[214:217], v[34:49]
	v_mfma_f32_32x32x16_bf16 v[18:33], v[124:127], v[214:217], v[18:33]
	s_waitcnt lgkmcnt(4)
	v_mfma_f32_32x32x16_bf16 v[2:17], v[128:131], v[214:217], v[2:17]
